# padded per-head bias table + ds_read2_b32 in cb64 near path; rotated cb64 key-tile sweep so the 9 units sharing a tile read it together
# speedup vs baseline: 1.0026x; 1.0026x over previous
; template <bool COOP>
; __global__ void __launch_bounds__(512, 2) mega(Args a) {
;     ...
;         for (int i = tid; i < NH * 257; i += 512) bias[i] = relb[i] * LOG2E;
;         __syncthreads();
.LBB0_324:
	global_load_dword v4, v[0:1], off
	v_add_u32_e32 v2, 0x200, v2
	v_cmp_lt_u32_e32 vcc, s6, v2
	v_lshl_add_u64 v[0:1], v[0:1], 0, s[4:5]
	s_or_b64 s[0:1], vcc, s[0:1]
	s_waitcnt vmcnt(0)
	v_mul_f32_e32 v4, 0x3fb8aa3b, v4
	ds_write_b32 v3, v4
	v_add_u32_e32 v3, 0x800, v3
	s_andn2_b64 exec, exec, s[0:1]
	s_cbranch_execnz .LBB0_324
	s_or_b64 exec, exec, s[0:1]
	v_add_u32_e32 v5, 0, v193
	v_lshrrev_b32_e32 v6, 6, v5
	v_mul_u32_u24_e32 v6, 13, v6
	v_lshrrev_b32_e32 v6, 6, v6
	v_mul_u32_u24_e32 v7, 0x140, v6
	v_sub_u32_e32 v7, v5, v7
	v_min_u32_e32 v7, 0x100, v7
	v_mul_u32_u24_e32 v6, 0x101, v6
	v_add_u32_e32 v7, v7, v6
	v_lshlrev_b32_e32 v7, 2, v7
	global_load_dword v8, v7, s[52:53]
	v_add_u32_e32 v5, 512, v193
	v_lshrrev_b32_e32 v6, 6, v5
	v_mul_u32_u24_e32 v6, 13, v6
	v_lshrrev_b32_e32 v6, 6, v6
	v_mul_u32_u24_e32 v7, 0x140, v6
	v_sub_u32_e32 v7, v5, v7
	v_min_u32_e32 v7, 0x100, v7
	v_mul_u32_u24_e32 v6, 0x101, v6
	v_add_u32_e32 v7, v7, v6
	v_lshlrev_b32_e32 v7, 2, v7
	global_load_dword v9, v7, s[52:53]
	v_add_u32_e32 v5, 1024, v193
	v_lshrrev_b32_e32 v6, 6, v5
	v_mul_u32_u24_e32 v6, 13, v6
	v_lshrrev_b32_e32 v6, 6, v6
	v_mul_u32_u24_e32 v7, 0x140, v6
	v_sub_u32_e32 v7, v5, v7
	v_min_u32_e32 v7, 0x100, v7
	v_mul_u32_u24_e32 v6, 0x101, v6
	v_add_u32_e32 v7, v7, v6
	v_lshlrev_b32_e32 v7, 2, v7
	global_load_dword v10, v7, s[52:53]
	v_add_u32_e32 v5, 1536, v193
	v_lshrrev_b32_e32 v6, 6, v5
	v_mul_u32_u24_e32 v6, 13, v6
	v_lshrrev_b32_e32 v6, 6, v6
	v_mul_u32_u24_e32 v7, 0x140, v6
	v_sub_u32_e32 v7, v5, v7
	v_min_u32_e32 v7, 0x100, v7
	v_mul_u32_u24_e32 v6, 0x101, v6
	v_add_u32_e32 v7, v7, v6
	v_lshlrev_b32_e32 v7, 2, v7
	global_load_dword v11, v7, s[52:53]
	v_add_u32_e32 v5, 2048, v193
	v_lshrrev_b32_e32 v6, 6, v5
	v_mul_u32_u24_e32 v6, 13, v6
	v_lshrrev_b32_e32 v6, 6, v6
	v_mul_u32_u24_e32 v7, 0x140, v6
	v_sub_u32_e32 v7, v5, v7
	v_min_u32_e32 v7, 0x100, v7
	v_mul_u32_u24_e32 v6, 0x101, v6
	v_add_u32_e32 v7, v7, v6
	v_lshlrev_b32_e32 v7, 2, v7
	global_load_dword v12, v7, s[52:53]
	s_waitcnt vmcnt(0)
	v_mul_f32_e32 v8, 0x3fb8aa3b, v8
	v_add_u32_e32 v5, 98304, v170
	ds_write_b32 v5, v8
	v_mul_f32_e32 v9, 0x3fb8aa3b, v9
	v_add_u32_e32 v5, 100352, v170
	ds_write_b32 v5, v9
	v_mul_f32_e32 v10, 0x3fb8aa3b, v10
	v_add_u32_e32 v5, 102400, v170
	ds_write_b32 v5, v10
	v_mul_f32_e32 v11, 0x3fb8aa3b, v11
	v_add_u32_e32 v5, 104448, v170
	ds_write_b32 v5, v11
	v_mul_f32_e32 v12, 0x3fb8aa3b, v12
	v_add_u32_e32 v5, 106496, v170
	ds_write_b32 v5, v12
	v_readlane_b32 s0, v255, 2
	v_readlane_b32 s1, v255, 3
	s_and_b64 vcc, exec, s[0:1]
	s_waitcnt lgkmcnt(0)
	s_barrier
	s_cbranch_vccnz .LBB0_327
	s_mov_b32 s10, 0
	s_movk_i32 s45, 0x400
	s_movk_i32 s92, 0x100
	s_movk_i32 s44, 0x1000
	s_branch .LBB0_328

; #define LAS __attribute__((address_space(3)))
; __device__ __forceinline__ void load_qfrags2(LAS unsigned char* vlds, const bf16_t* q0, int lane, bf16x8 (&qfA)[4], bf16x8 (&qfB)[4]) {
;     asm volatile("" : "+v"(lane));
;     const int r32 = lane & 31, hi = lane >> 5;
;     u32x4 pa[4], pb[4];
; #pragma unroll
;     for (int i = 0; i < 4; ++i) { const int id = lane + 64 * i; const bf16_t* p = q0 + (size_t)(id >> 3) * 512 + (id & 7) * 8; pa[i] = *(const u32x4*)p; pb[i] = *(const u32x4*)(p + 32 * 512); }
;     asm volatile("" ::: "memory");
; #pragma unroll
;     for (int i = 0; i < 4; ++i) { const int id = lane + 64 * i; *(LAS u32x4*)(vlds + 4096 + (id >> 3) * 144 + (id & 7) * 16) = pa[i]; }
;     asm volatile("" ::: "memory");
; #pragma unroll
;     for (int i = 0; i < 4; ++i) qfA[i] = *(const LAS bf16x8*)(vlds + 4096 + r32 * 144 + (2 * i + hi) * 16);
;     asm volatile("" ::: "memory");
; #pragma unroll
;     for (int i = 0; i < 4; ++i) { const int id = lane + 64 * i; *(LAS u32x4*)(vlds + 4096 + (id >> 3) * 144 + (id & 7) * 16) = pb[i]; }
;     asm volatile("" ::: "memory");
; #pragma unroll
;     for (int i = 0; i < 4; ++i) qfB[i] = *(const LAS bf16x8*)(vlds + 4096 + r32 * 144 + (2 * i + hi) * 16);
;     asm volatile("" ::: "memory");
; __device__ __forceinline__ void attn_unit_cb64(const AttnCtx& C, int b, int h, int c, LAS unsigned char* vlds, const LAS float* bias_h, int lane) {
;     const int r32 = lane & 31, hi = lane >> 5;
;     const size_t qrowA = (size_t)b * TT + c * 64 + r32;
;     const int qposA = c * 64 + r32;
;     const int s_hi = c * 64 + 32; int s_lo = (c - 8) * 64; if (s_lo < 0) s_lo = 0;
;     bf16x8 qfA[4], qfB[4];
;     u32x4 kr[4], vr[4];
;     load_tile<false>(C, false, b, h, s_hi, lane, kr, vr);
;     load_qfrags2(vlds, C.QCB + ((size_t)b * TT + c * 64) * 512 + h * 64, lane, qfA, qfB);
;     f32x16 oA0 = {}, oA1 = {}, oB0 = {}, oB1 = {};
;     float mA = -1e30f, lA = 0.f, mB = -1e30f, lB = 0.f;
;     const float bfar = bias_h[256];
;     LAS unsigned char* trb = vlds + (4 * hi + ((lane & 15) >> 2)) * 64 + ((lane >> 4) & 1) * 32 + (lane & 3) * 8;
.LBB0_390:
	s_and_b64 vcc, exec, s[8:9]
	s_cbranch_vccz .LBB0_408
	s_bfe_u32 s17, s81, 0x30006
	s_ashr_i32 s8, s81, 9
	s_mul_i32 s9, s17, 0x404
	s_add_i32 s14, s9, 0
	s_ashr_i32 s9, s8, 31
	s_lshl_b32 s20, s80, 6
	s_lshl_b64 s[10:11], s[8:9], 12
	s_or_b32 s15, s20, 32
	s_mul_i32 s98, s80, 57
	s_lshr_b32 s98, s98, 9
	s_mul_i32 s98, s98, 9
	s_sub_i32 s98, s80, s98
	s_lshl_b32 s98, s98, 1
	s_cmp_lt_u32 s80, 8
	s_cselect_b32 s98, 0, s98
	s_lshl_b32 s99, s98, 5
	s_sub_i32 s15, s15, s99
	s_or_b32 s12, s10, s20
	s_or_b32 s10, s10, s15
	s_add_i32 s14, s14, 0x14000
	s_mov_b32 s13, s11
	s_lshl_b64 s[10:11], s[10:11], 10
	s_add_u32 s18, s78, s10
	s_addc_u32 s19, s79, s11
	s_lshl_b32 s16, s17, 6
	s_lshl_b32 s17, s17, 7
	s_add_u32 s18, s18, s17
	s_addc_u32 s19, s19, 0
	v_lshlrev_b32_e32 v0, 1, v196
	s_add_u32 s10, s88, s10
	v_lshl_add_u64 v[2:3], s[18:19], 0, v[0:1]
	v_lshlrev_b32_e32 v4, 1, v194
	v_mov_b32_e32 v5, v1
	s_addc_u32 s11, s89, s11
	v_lshl_add_u64 v[6:7], v[2:3], 0, v[4:5]
	v_lshlrev_b32_e32 v8, 1, v198
	v_mov_b32_e32 v9, v1
	v_lshl_add_u64 v[10:11], v[2:3], 0, v[8:9]
	global_load_dwordx4 v[144:147], v[6:7], off
	global_load_dwordx4 v[128:131], v[10:11], off
	v_lshlrev_b32_e32 v6, 1, v200
	v_mov_b32_e32 v7, v1
	v_lshlrev_b32_e32 v12, 1, v202
	v_mov_b32_e32 v13, v1
	s_add_u32 s10, s10, s17
	v_lshl_add_u64 v[10:11], v[2:3], 0, v[6:7]
	v_lshl_add_u64 v[2:3], v[2:3], 0, v[12:13]
	s_addc_u32 s11, s11, 0
	global_load_dwordx4 v[132:135], v[10:11], off
	global_load_dwordx4 v[136:139], v[2:3], off
	v_lshl_add_u64 v[2:3], s[10:11], 0, v[0:1]
	s_lshl_b64 s[10:11], s[12:13], 10
	v_lshl_add_u64 v[4:5], v[2:3], 0, v[4:5]
	s_add_u32 s12, s95, s10
	v_lshl_add_u64 v[8:9], v[2:3], 0, v[8:9]
	global_load_dwordx4 v[140:143], v[4:5], off
	global_load_dwordx4 v[148:151], v[8:9], off
	v_lshl_add_u64 v[4:5], v[2:3], 0, v[6:7]
	s_addc_u32 s13, s96, s11
	v_mov_b32_e32 v42, v192
	v_lshl_add_u64 v[2:3], v[2:3], 0, v[12:13]
	global_load_dwordx4 v[152:155], v[4:5], off
	global_load_dwordx4 v[156:159], v[2:3], off
	s_add_u32 s12, s12, s17
	s_addc_u32 s13, s13, 0
	v_lshlrev_b32_e32 v0, 4, v42
	v_ashrrev_i32_e32 v34, 3, v42
	v_and_b32_e32 v0, 0x70, v0
	v_ashrrev_i32_e32 v35, 31, v34
	v_add_u32_e32 v10, 64, v42
	v_add_u32_e32 v14, 0x80, v42
	v_lshl_add_u64 v[18:19], s[12:13], 0, v[0:1]
	v_lshlrev_b64 v[2:3], 10, v[34:35]
	v_ashrrev_i32_e32 v36, 3, v10
	v_ashrrev_i32_e32 v38, 3, v14
	v_add_u32_e32 v20, 0xc0, v42
	v_lshl_add_u64 v[2:3], v[18:19], 0, v[2:3]
	v_ashrrev_i32_e32 v37, 31, v36
	v_ashrrev_i32_e32 v39, 31, v38
	v_ashrrev_i32_e32 v40, 3, v20
	v_add_co_u32_e32 v6, vcc, s77, v2
	v_lshlrev_b64 v[10:11], 10, v[36:37]
	v_lshlrev_b64 v[14:15], 10, v[38:39]
	v_ashrrev_i32_e32 v41, 31, v40
	v_addc_co_u32_e32 v7, vcc, 0, v3, vcc
	v_lshl_add_u64 v[22:23], v[18:19], 0, v[10:11]
	v_lshl_add_u64 v[26:27], v[18:19], 0, v[14:15]
	v_lshlrev_b64 v[20:21], 10, v[40:41]
	global_load_dwordx4 v[2:5], v[2:3], off
	s_nop 0
	global_load_dwordx4 v[6:9], v[6:7], off
	v_lshl_add_u64 v[30:31], v[18:19], 0, v[20:21]
	global_load_dwordx4 v[10:13], v[22:23], off
	global_load_dwordx4 v[14:17], v[26:27], off
	v_add_co_u32_e32 v22, vcc, s77, v22
	global_load_dwordx4 v[18:21], v[30:31], off
	s_nop 0
	v_addc_co_u32_e32 v23, vcc, 0, v23, vcc
	v_add_co_u32_e32 v26, vcc, s77, v26
	global_load_dwordx4 v[22:25], v[22:23], off
	s_nop 0
	v_addc_co_u32_e32 v27, vcc, 0, v27, vcc
	v_add_co_u32_e32 v30, vcc, s77, v30
	global_load_dwordx4 v[26:29], v[26:27], off
	s_nop 0
	v_addc_co_u32_e32 v31, vcc, 0, v31, vcc
	global_load_dwordx4 v[30:33], v[30:31], off
	v_add_u32_e32 v0, s94, v0
	v_mad_u64_u32 v[34:35], s[12:13], v34, s82, v[0:1]
	v_and_b32_e32 v37, 31, v42
	s_lshl_b64 s[8:9], s[8:9], 22
	v_sub_u32_e64 v230, s20, v245 clamp
	v_mov_b32_e32 v231, 0xf149f2ca
	v_mov_b32_e32 v228, 0
	v_mov_b32_e32 v229, 0
	v_mov_b32_e32 v232, 0xf149f2ca
	s_waitcnt vmcnt(7)
	ds_write_b128 v34, v[2:5] offset:4096
	v_mad_u64_u32 v[2:3], s[12:13], v36, s82, v[0:1]
	s_waitcnt vmcnt(5)
	ds_write_b128 v2, v[10:13] offset:4096
	v_mad_u64_u32 v[4:5], s[12:13], v38, s82, v[0:1]
	v_mad_u64_u32 v[10:11], s[12:13], v40, s82, v[0:1]
	v_ashrrev_i32_e32 v3, 1, v42
	s_waitcnt vmcnt(4)
	ds_write_b128 v4, v[14:17] offset:4096
	s_waitcnt vmcnt(3)
	ds_write_b128 v10, v[18:21] offset:4096
	v_mul_u32_u24_e32 v0, 0x90, v37
	v_and_b32_e32 v3, -16, v3
	v_add3_u32 v0, s94, v0, v3
	ds_read_b128 v[160:163], v0 offset:4096
	ds_read_b128 v[164:167], v0 offset:4128
	ds_read_b128 v[168:171], v0 offset:4160
	ds_read_b128 v[172:175], v0 offset:4192
	ds_write_b128 v34, v[6:9] offset:4096
	s_waitcnt vmcnt(2)
	ds_write_b128 v2, v[22:25] offset:4096
	s_waitcnt vmcnt(1)
	ds_write_b128 v4, v[26:29] offset:4096
	s_waitcnt vmcnt(0)
	ds_write_b128 v10, v[30:33] offset:4096
	ds_read_b128 v[176:179], v0 offset:4096
	ds_read_b128 v[180:183], v0 offset:4128
	ds_read_b128 v[184:187], v0 offset:4160
	ds_read_b128 v[188:191], v0 offset:4192
	v_mov_b32_e32 v0, s14
	ds_read_b32 v222, v0 offset:1024
	s_mul_i32 s14, s16, 20
	s_add_i32 s14, s14, 0x18000
	s_add_i32 s12, s92, s33
	s_and_b32 s12, s12, 63
	s_lshl_b32 s12, s12, 16
	s_or_b32 s8, s8, s12
	v_mov_b32_e32 v14, v1
	v_mov_b32_e32 v15, v1
	s_or_b32 s8, s8, s17
	v_mov_b32_e32 v0, v1
	v_mov_b32_e32 v2, v1
	v_mov_b32_e32 v3, v1
	v_mov_b32_e32 v4, v1
	v_mov_b32_e32 v5, v1
	v_mov_b32_e32 v6, v1
	v_mov_b32_e32 v7, v1
	v_mov_b32_e32 v8, v1
	v_mov_b32_e32 v9, v1
	v_mov_b32_e32 v10, v1
	v_mov_b32_e32 v11, v1
	v_mov_b32_e32 v12, v1
	v_mov_b32_e32 v13, v1
	v_mov_b64_e32 v[30:31], v[14:15]
	v_mov_b64_e32 v[46:47], v[14:15]
	v_mov_b64_e32 v[62:63], v[14:15]
	v_mov_b64_e32 v[78:79], v[14:15]
	s_waitcnt lgkmcnt(0)
	v_mov_b32_e32 v224, v222
	v_mov_b32_e32 v225, v222
	s_lshl_b32 s99, s98, 15
	s_sub_u32 s8, s8, s99
	s_subb_u32 s9, s9, 0
	v_lshl_add_u64 v[226:227], v[220:221], 0, s[8:9]
	s_movk_i32 s17, 0xffc1
	s_lshl_b32 s99, s98, 5
	s_add_i32 s17, s17, s99
	v_mov_b64_e32 v[28:29], v[12:13]
	v_mov_b64_e32 v[26:27], v[10:11]
	v_mov_b64_e32 v[24:25], v[8:9]
	v_mov_b64_e32 v[22:23], v[6:7]
	v_mov_b64_e32 v[20:21], v[4:5]
	v_mov_b64_e32 v[18:19], v[2:3]
	v_mov_b64_e32 v[16:17], v[0:1]
	v_mov_b64_e32 v[44:45], v[12:13]
	v_mov_b64_e32 v[42:43], v[10:11]
	v_mov_b64_e32 v[40:41], v[8:9]
	v_mov_b64_e32 v[38:39], v[6:7]
	v_mov_b64_e32 v[36:37], v[4:5]
	v_mov_b64_e32 v[34:35], v[2:3]
	v_mov_b64_e32 v[32:33], v[0:1]
	v_mov_b64_e32 v[60:61], v[12:13]
	v_mov_b64_e32 v[58:59], v[10:11]
	v_mov_b64_e32 v[56:57], v[8:9]
	v_mov_b64_e32 v[54:55], v[6:7]
	v_mov_b64_e32 v[52:53], v[4:5]
	v_mov_b64_e32 v[50:51], v[2:3]
	v_mov_b64_e32 v[48:49], v[0:1]
	v_mov_b64_e32 v[76:77], v[12:13]
	v_mov_b64_e32 v[74:75], v[10:11]
	v_mov_b64_e32 v[72:73], v[8:9]
	v_mov_b64_e32 v[70:71], v[6:7]
	v_mov_b64_e32 v[68:69], v[4:5]
	v_mov_b64_e32 v[66:67], v[2:3]
	v_mov_b64_e32 v[64:65], v[0:1]
	s_branch .LBB0_393

; __device__ __forceinline__ void cb_soft(const f32x16& s, int s0, int qpos, float bfar, const LAS float* bias_h, int lane, f32x16& o0, f32x16& o1, float& mrun, float& lrun, bf16x8 (&pf)[2]) {
;     ...
;         const int dq = qpos - s0 - 4 * hi + 128;
; #pragma unroll
;         for (int r = 0; r < 16; ++r) { int d = dq - ((r & 3) + 8 * (r >> 2)); d = d < 0 ? 0 : (d > 256 ? 256 : d); p[r] = s[r] + bias_h[d]; }
.LBB0_395:
	s_mov_b64 s[12:13], -1
	s_cmpk_lt_i32 s17, 0x80
	v_add_u32_e32 v0, s17, v241
	s_cbranch_scc0 .LBB0_397
	v_lshl_add_u32 v10, v0, 2, s14
	ds_read2_b32 v[8:9], v10 offset0:133 offset1:132
	ds_read2_b32 v[6:7], v10 offset0:135 offset1:134
	ds_read2_b32 v[4:5], v10 offset0:141 offset1:140
	ds_read2_b32 v[2:3], v10 offset0:143 offset1:142
	ds_read2_b32 v[80:81], v10 offset0:149 offset1:148
	ds_read2_b32 v[14:15], v10 offset0:151 offset1:150
	ds_read2_b32 v[12:13], v10 offset0:157 offset1:156
	ds_read2_b32 v[10:11], v10 offset0:159 offset1:158
	s_waitcnt lgkmcnt(4)
	v_pk_add_f32 v[94:95], v[126:127], v[8:9]
	v_pk_add_f32 v[92:93], v[124:125], v[6:7]
	v_pk_add_f32 v[90:91], v[122:123], v[4:5]
	v_pk_add_f32 v[88:89], v[120:121], v[2:3]
	s_waitcnt lgkmcnt(0)
	v_pk_add_f32 v[86:87], v[118:119], v[80:81]
	v_pk_add_f32 v[84:85], v[116:117], v[14:15]
	v_pk_add_f32 v[82:83], v[114:115], v[12:13]
	v_pk_add_f32 v[80:81], v[112:113], v[10:11]
	s_cbranch_execz .LBB0_398
	s_branch .LBB0_399

; __device__ __forceinline__ void cb_soft(const f32x16& s, int s0, int qpos, float bfar, const LAS float* bias_h, int lane, f32x16& o0, f32x16& o1, float& mrun, float& lrun, bf16x8 (&pf)[2]) {
;     ...
;         const int dq = qpos - s0 - 4 * hi + 128;
; #pragma unroll
;         for (int r = 0; r < 16; ++r) { int d = dq - ((r & 3) + 8 * (r >> 2)); d = d < 0 ? 0 : (d > 256 ? 256 : d); p[r] = s[r] + bias_h[d]; }
.LBB0_401:
	s_add_i32 s17, s17, 32
	s_cmpk_lt_i32 s17, 0x80
	s_mov_b64 s[12:13], -1
	s_cbranch_scc0 .LBB0_403
	v_lshl_add_u32 v10, v0, 2, s14
	ds_read2_b32 v[8:9], v10 offset0:165 offset1:164
	ds_read2_b32 v[6:7], v10 offset0:167 offset1:166
	ds_read2_b32 v[4:5], v10 offset0:173 offset1:172
	ds_read2_b32 v[2:3], v10 offset0:175 offset1:174
	ds_read2_b32 v[114:115], v10 offset0:181 offset1:180
	ds_read2_b32 v[112:113], v10 offset0:183 offset1:182
	ds_read2_b32 v[12:13], v10 offset0:189 offset1:188
	ds_read2_b32 v[10:11], v10 offset0:191 offset1:190
	s_waitcnt lgkmcnt(4)
	v_pk_add_f32 v[126:127], v[110:111], v[8:9]
	v_pk_add_f32 v[124:125], v[108:109], v[6:7]
	v_pk_add_f32 v[122:123], v[106:107], v[4:5]
	v_pk_add_f32 v[120:121], v[104:105], v[2:3]
	s_waitcnt lgkmcnt(0)
	v_pk_add_f32 v[118:119], v[102:103], v[114:115]
	v_pk_add_f32 v[116:117], v[100:101], v[112:113]
	v_pk_add_f32 v[114:115], v[98:99], v[12:13]
	v_pk_add_f32 v[112:113], v[96:97], v[10:11]
	s_mov_b64 s[12:13], 0

; template <bool SB>
; __device__ __forceinline__ void load_tile(const AttnCtx& C, bool sample, int b, int h, int s0, int lane, u32x4 (&kr)[4], u32x4 (&vr)[4]) {
;     if (!sample || s0 >= PAST) {
; __device__ __forceinline__ void attn_unit_cb64(const AttnCtx& C, int b, int h, int c, LAS unsigned char* vlds, const LAS float* bias_h, int lane) {
;     ...
;     for (int s0 = s_hi;; s0 -= 32) {
;         asm volatile("" ::: "memory");
; #pragma unroll
;         for (int i = 0; i < 4; ++i) { const int id = lane + 64 * i, key = id >> 3, cc = id & 7; *(LAS u32x4*)(vlds + (cc >> 2) * 2048 + key * 64 + (cc & 3) * 16) = vr[i]; }
; #pragma unroll
;         for (int i = 0; i < 4; ++i) { const int id = lane + 64 * i, key = id >> 3, cc = id & 7; *(LAS u32x4*)(vlds + 4096 + key * 144 + cc * 16) = kr[i]; }
;         asm volatile("" ::: "memory");
;         bf16x8 kf[4];
; #pragma unroll
;         for (int i = 0; i < 4; ++i) kf[i] = *(const LAS bf16x8*)(vlds + 4096 + r32 * 144 + (2 * i + hi) * 16);
;         f32x16 sA = {}, sB = {};
; #pragma unroll
;         for (int i = 0; i < 4; ++i) { sA = __builtin_amdgcn_mfma_f32_32x32x16_bf16(kf[i], qfA[i], sA, 0, 0, 0); sB = __builtin_amdgcn_mfma_f32_32x32x16_bf16(kf[i], qfB[i], sB, 0, 0, 0); }
;         if (s0 - 32 >= s_lo) load_tile<false>(C, false, b, h, s0 - 32, lane, kr, vr);
;         bf16x8 pfA[2], pfB[2];
;         cb_soft(sA, s0, qposA, bfar, bias_h, lane, oA0, oA1, mA, lA, pfA);
;         cb_soft(sB, s0, qposA + 32, bfar, bias_h, lane, oB0, oB1, mB, lB, pfB);
;         asm volatile("" ::: "memory");
; #pragma unroll
;         for (int ks = 0; ks < 2; ++ks) {
;             const s16x4 a0 = vtr(trb + ks * 1024), a1 = vtr(trb + ks * 1024 + 512), b0 = vtr(trb + 2048 + ks * 1024), b1 = vtr(trb + 2048 + ks * 1024 + 512);
;             const bf16x8 v0 = (bf16x8){a0[0], a0[1], a0[2], a0[3], a1[0], a1[1], a1[2], a1[3]}, v1 = (bf16x8){b0[0], b0[1], b0[2], b0[3], b1[0], b1[1], b1[2], b1[3]};
;             oA0 = __builtin_amdgcn_mfma_f32_32x32x16_bf16(v0, pfA[ks], oA0, 0, 0, 0); oA1 = __builtin_amdgcn_mfma_f32_32x32x16_bf16(v1, pfA[ks], oA1, 0, 0, 0);
;             oB0 = __builtin_amdgcn_mfma_f32_32x32x16_bf16(v0, pfB[ks], oB0, 0, 0, 0); oB1 = __builtin_amdgcn_mfma_f32_32x32x16_bf16(v1, pfB[ks], oB1, 0, 0, 0);
;         }
;         asm volatile("" ::: "memory");
;         if (s0 - 32 < s_lo) break;
.LBB0_407:
	s_cmp_eq_u32 s98, 0
	s_cbranch_scc1 .Lcb_nowrap
	s_lshl_b32 s100, s80, 6
	s_or_b32 s15, s100, 32
	s_lshl_b32 s100, s98, 5
	s_sub_i32 s100, s15, s100
	s_add_i32 s100, s100, 32
	v_mov_b32_e32 v230, s100
	s_movk_i32 s17, 0xffc1
	s_mov_b32 s98, 0
	s_mov_b32 s100, 0x98000
	s_mov_b32 s101, 0
	v_lshl_add_u64 v[226:227], v[226:227], 0, s[100:101]
	v_add_co_u32_e32 v2, vcc, 0x2000, v226
	s_nop 1
	v_addc_co_u32_e32 v3, vcc, 0, v227, vcc
	v_add_co_u32_e32 v4, vcc, 0x4000, v226
	s_nop 1
	v_addc_co_u32_e32 v5, vcc, 0, v227, vcc
	global_load_dwordx4 v[128:131], v[2:3], off
	global_load_dwordx4 v[132:135], v[4:5], off
	v_add_co_u32_e32 v2, vcc, 0x6000, v226
	s_nop 1
	v_addc_co_u32_e32 v3, vcc, 0, v227, vcc
	v_add_co_u32_e32 v4, vcc, 0x2100000, v226
	s_nop 1
	v_addc_co_u32_e32 v5, vcc, 0, v227, vcc
	global_load_dwordx4 v[136:139], v[2:3], off
	global_load_dwordx4 v[140:143], v[4:5], off
	v_add_co_u32_e32 v2, vcc, 0x2102000, v226
	s_nop 1
	v_addc_co_u32_e32 v3, vcc, 0, v227, vcc
	v_add_co_u32_e32 v4, vcc, 0x2104000, v226
	s_nop 1
	v_addc_co_u32_e32 v5, vcc, 0, v227, vcc
	global_load_dwordx4 v[148:151], v[2:3], off
	global_load_dwordx4 v[152:155], v[4:5], off
	v_add_co_u32_e32 v2, vcc, 0x2106000, v226
	s_nop 1
	v_addc_co_u32_e32 v3, vcc, 0, v227, vcc
	global_load_dwordx4 v[144:147], v[226:227], off
	global_load_dwordx4 v[156:159], v[2:3], off
	s_mov_b32 s100, 0xffff8000
	s_mov_b32 s101, -1
	v_lshl_add_u64 v[226:227], v[226:227], 0, s[100:101]
	s_branch .LBB0_393

; template <bool COOP>
; __global__ void __launch_bounds__(512, 2) mega(Args a) {
	.amdhsa_kernel _Z4megaILb1EEv4Args
		.amdhsa_group_segment_fixed_size 0
		.amdhsa_private_segment_fixed_size 0
		.amdhsa_kernarg_size 392
		.amdhsa_user_sgpr_count 2
		.amdhsa_user_sgpr_dispatch_ptr 0
		.amdhsa_user_sgpr_queue_ptr 0
		.amdhsa_user_sgpr_kernarg_segment_ptr 1
		.amdhsa_user_sgpr_dispatch_id 0
		.amdhsa_user_sgpr_kernarg_preload_length 0
		.amdhsa_user_sgpr_kernarg_preload_offset 0
		.amdhsa_user_sgpr_private_segment_size 0
		.amdhsa_uses_dynamic_stack 0
		.amdhsa_enable_private_segment 0
		.amdhsa_system_sgpr_workgroup_id_x 1
		.amdhsa_system_sgpr_workgroup_id_y 0
		.amdhsa_system_sgpr_workgroup_id_z 0
		.amdhsa_system_sgpr_workgroup_info 0
		.amdhsa_system_vgpr_workitem_id 2
		.amdhsa_next_free_vgpr 256
		.amdhsa_next_free_sgpr 102
		.amdhsa_accum_offset 256
		.amdhsa_reserve_vcc 1
		.amdhsa_float_round_mode_32 0
		.amdhsa_float_round_mode_16_64 0
		.amdhsa_float_denorm_mode_32 3
		.amdhsa_float_denorm_mode_16_64 3
		.amdhsa_dx10_clamp 1
		.amdhsa_ieee_mode 1
		.amdhsa_fp16_overflow 0
		.amdhsa_tg_split 0
		.amdhsa_exception_fp_ieee_invalid_op 0
		.amdhsa_exception_fp_denorm_src 0
		.amdhsa_exception_fp_ieee_div_zero 0
		.amdhsa_exception_fp_ieee_overflow 0
		.amdhsa_exception_fp_ieee_underflow 0
		.amdhsa_exception_fp_ieee_inexact 0
		.amdhsa_exception_int_div_zero 0
	.end_amdhsa_kernel

; template <bool COOP>
; __global__ void __launch_bounds__(512, 2) mega(Args a) {
amdhsa.kernels:
  - .agpr_count:     0
    .args:
      - .offset:         0
        .size:           136
        .value_kind:     by_value
      - .offset:         136
        .size:           4
        .value_kind:     hidden_block_count_x
      - .offset:         140
        .size:           4
        .value_kind:     hidden_block_count_y
      - .offset:         144
        .size:           4
        .value_kind:     hidden_block_count_z
      - .offset:         148
        .size:           2
        .value_kind:     hidden_group_size_x
      - .offset:         150
        .size:           2
        .value_kind:     hidden_group_size_y
      - .offset:         152
        .size:           2
        .value_kind:     hidden_group_size_z
      - .offset:         154
        .size:           2
        .value_kind:     hidden_remainder_x
      - .offset:         156
        .size:           2
        .value_kind:     hidden_remainder_y
      - .offset:         158
        .size:           2
        .value_kind:     hidden_remainder_z
      - .offset:         176
        .size:           8
        .value_kind:     hidden_global_offset_x
      - .offset:         184
        .size:           8
        .value_kind:     hidden_global_offset_y
      - .offset:         192
        .size:           8
        .value_kind:     hidden_global_offset_z
      - .offset:         200
        .size:           2
        .value_kind:     hidden_grid_dims
      - .offset:         224
        .size:           8
        .value_kind:     hidden_multigrid_sync_arg
      - .offset:         256
        .size:           4
        .value_kind:     hidden_dynamic_lds_size
    .group_segment_fixed_size: 0
    .kernarg_segment_align: 8
    .kernarg_segment_size: 392
    .language:       OpenCL C
    .language_version:
      - 2
      - 0
    .max_flat_workgroup_size: 512
    .name:           _Z4megaILb1EEv4Args
    .private_segment_fixed_size: 0
    .sgpr_count:     108
    .sgpr_spill_count: 28
    .symbol:         _Z4megaILb1EEv4Args.kd
    .uniform_work_group_size: 1
    .uses_dynamic_stack: false
    .vgpr_count:     256
    .vgpr_spill_count: 0
    .wavefront_size: 64
